# attention unit epilogue: the 16 sub-LN weight loads hoisted to the section start (were 8 load-pair/vmcnt(0)/store rounds)
# speedup vs baseline: 1.0058x; 1.0058x over previous
.LBB0_273:
	s_and_b64 vcc, exec, s[38:39]
	s_waitcnt lgkmcnt(0)
	s_barrier
	s_cbranch_vccnz .LBB0_164
	v_lshlrev_b32_e32 v1, 6, v166
	v_ashrrev_i32_e32 v65, 1, v166
	v_and_b32_e32 v64, 64, v1
	v_lshlrev_b32_e32 v0, 9, v65
	v_lshlrev_b32_e32 v71, 2, v64
	global_load_dwordx4 v[130:133], v71, s[72:73]
	global_load_dwordx4 v[134:137], v71, s[72:73] offset:16
	global_load_dwordx4 v[138:141], v71, s[72:73] offset:32
	global_load_dwordx4 v[142:145], v71, s[72:73] offset:48
	global_load_dwordx4 v[146:149], v71, s[72:73] offset:64
	global_load_dwordx4 v[150:153], v71, s[72:73] offset:80
	global_load_dwordx4 v[154:157], v71, s[72:73] offset:96
	global_load_dwordx4 v[158:161], v71, s[72:73] offset:112
	global_load_dwordx4 v[168:171], v71, s[72:73] offset:128
	global_load_dwordx4 v[172:175], v71, s[72:73] offset:144
	global_load_dwordx4 v[176:179], v71, s[72:73] offset:160
	global_load_dwordx4 v[180:183], v71, s[72:73] offset:176
	global_load_dwordx4 v[184:187], v71, s[72:73] offset:192
	global_load_dwordx4 v[188:191], v71, s[72:73] offset:208
	global_load_dwordx4 v[192:195], v71, s[72:73] offset:224
	global_load_dwordx4 v[196:199], v71, s[72:73] offset:240
	v_add3_u32 v52, s3, v0, v71
	ds_read_b128 v[60:63], v52
	ds_read_b128 v[20:23], v52 offset:16
	ds_read_b128 v[12:15], v52 offset:32
	ds_read_b128 v[0:3], v52 offset:48
	ds_read_b128 v[16:19], v52 offset:64
	s_waitcnt lgkmcnt(4)
	v_pk_mul_f32 v[4:5], v[62:63], v[62:63]
	v_pk_mul_f32 v[6:7], v[60:61], v[60:61]
	v_cmp_lt_i32_e32 vcc, v235, v234
	v_pk_mov_b32 v[8:9], v[6:7], v[4:5] op_sel:[1,0]
	v_mov_b32_e32 v7, v5
	v_pk_add_f32 v[4:5], v[8:9], v[6:7]
	s_waitcnt lgkmcnt(3)
	v_pk_mul_f32 v[6:7], v[22:23], v[22:23]
	v_pk_mul_f32 v[8:9], v[20:21], v[20:21]
	v_pk_add_f32 v[4:5], v[4:5], v[4:5] op_sel:[0,1] op_sel_hi:[1,0]
	v_pk_mov_b32 v[10:11], v[8:9], v[6:7] op_sel:[1,0]
	v_mov_b32_e32 v9, v7
	v_pk_add_f32 v[6:7], v[10:11], v[8:9]
	s_waitcnt lgkmcnt(1)
	v_mul_f32_e32 v8, v0, v0
	v_mul_f32_e32 v9, v1, v1
	v_pk_add_f32 v[6:7], v[6:7], v[6:7] op_sel:[0,1] op_sel_hi:[1,0]
	v_mov_b32_e32 v5, v8
	v_mov_b32_e32 v7, v9
	v_pk_add_f32 v[4:5], v[4:5], v[6:7]
	v_mul_f32_e32 v6, v13, v13
	v_mul_f32_e32 v8, v15, v15
	v_mul_f32_e32 v10, v2, v2
	v_mul_f32_e32 v11, v3, v3
	v_pk_fma_f32 v[6:7], v[12:13], v[12:13], v[6:7] op_sel_hi:[1,1,0]
	v_pk_fma_f32 v[8:9], v[14:15], v[14:15], v[8:9] op_sel_hi:[1,1,0]
	v_mov_b32_e32 v7, v10
	v_mov_b32_e32 v9, v11
	v_pk_add_f32 v[6:7], v[6:7], v[8:9]
	v_lshlrev_b32_e32 v128, 1, v64
	v_pk_add_f32 v[24:25], v[4:5], v[6:7]
	s_waitcnt lgkmcnt(0)
	v_pk_mul_f32 v[4:5], v[18:19], v[18:19]
	v_pk_mul_f32 v[6:7], v[16:17], v[16:17]
	v_pk_add_f32 v[24:25], v[24:25], v[24:25] op_sel:[0,1] op_sel_hi:[1,0]
	v_pk_mov_b32 v[8:9], v[6:7], v[4:5] op_sel:[1,0]
	v_mov_b32_e32 v7, v5
	v_pk_add_f32 v[26:27], v[8:9], v[6:7]
	ds_read_b128 v[4:7], v52 offset:80
	ds_read_b128 v[8:11], v52 offset:96
	v_pk_add_f32 v[26:27], v[26:27], v[26:27] op_sel:[0,1] op_sel_hi:[1,0]
	s_waitcnt lgkmcnt(0)
	v_mul_f32_e32 v28, v8, v8
	v_mul_f32_e32 v29, v9, v9
	v_mov_b32_e32 v25, v28
	v_mov_b32_e32 v27, v29
	v_pk_add_f32 v[24:25], v[24:25], v[26:27]
	v_mul_f32_e32 v26, v5, v5
	v_mul_f32_e32 v28, v7, v7
	v_mul_f32_e32 v30, v10, v10
	v_mul_f32_e32 v31, v11, v11
	v_pk_fma_f32 v[26:27], v[4:5], v[4:5], v[26:27] op_sel_hi:[1,1,0]
	v_pk_fma_f32 v[28:29], v[6:7], v[6:7], v[28:29] op_sel_hi:[1,1,0]
	v_mov_b32_e32 v27, v30
	v_mov_b32_e32 v29, v31
	v_pk_add_f32 v[26:27], v[26:27], v[28:29]
	s_nop 0
	v_pk_add_f32 v[32:33], v[24:25], v[26:27]
	ds_read_b128 v[24:27], v52 offset:112
	v_pk_add_f32 v[32:33], v[32:33], v[32:33] op_sel:[0,1] op_sel_hi:[1,0]
	s_waitcnt lgkmcnt(0)
	v_pk_mul_f32 v[28:29], v[26:27], v[26:27]
	v_pk_mul_f32 v[30:31], v[24:25], v[24:25]
	s_nop 0
	v_pk_mov_b32 v[34:35], v[30:31], v[28:29] op_sel:[1,0]
	v_mov_b32_e32 v31, v29
	v_pk_add_f32 v[34:35], v[34:35], v[30:31]
	ds_read_b128 v[40:43], v52 offset:128
	ds_read_b128 v[28:31], v52 offset:144
	v_pk_add_f32 v[34:35], v[34:35], v[34:35] op_sel:[0,1] op_sel_hi:[1,0]
	ds_read_b128 v[44:47], v52 offset:160
	s_waitcnt lgkmcnt(1)
	v_mul_f32_e32 v36, v28, v28
	v_mul_f32_e32 v37, v29, v29
	v_mov_b32_e32 v33, v36
	v_mov_b32_e32 v35, v37
	v_pk_add_f32 v[32:33], v[32:33], v[34:35]
	v_mul_f32_e32 v34, v41, v41
	v_mul_f32_e32 v36, v43, v43
	v_mul_f32_e32 v38, v30, v30
	v_mul_f32_e32 v39, v31, v31
	v_pk_fma_f32 v[34:35], v[40:41], v[40:41], v[34:35] op_sel_hi:[1,1,0]
	v_pk_fma_f32 v[36:37], v[42:43], v[42:43], v[36:37] op_sel_hi:[1,1,0]
	v_mov_b32_e32 v35, v38
	v_mov_b32_e32 v37, v39
	v_pk_add_f32 v[34:35], v[34:35], v[36:37]
	s_nop 0
	v_pk_add_f32 v[48:49], v[32:33], v[34:35]
	s_waitcnt lgkmcnt(0)
	v_pk_mul_f32 v[32:33], v[46:47], v[46:47]
	v_pk_mul_f32 v[34:35], v[44:45], v[44:45]
	v_pk_add_f32 v[48:49], v[48:49], v[48:49] op_sel:[0,1] op_sel_hi:[1,0]
	v_pk_mov_b32 v[36:37], v[34:35], v[32:33] op_sel:[1,0]
	v_mov_b32_e32 v35, v33
	v_pk_add_f32 v[50:51], v[36:37], v[34:35]
	ds_read_b128 v[32:35], v52 offset:176
	ds_read_b128 v[36:39], v52 offset:192
	v_pk_add_f32 v[50:51], v[50:51], v[50:51] op_sel:[0,1] op_sel_hi:[1,0]
	s_waitcnt lgkmcnt(0)
	v_mul_f32_e32 v53, v36, v36
	v_mul_f32_e32 v54, v37, v37
	v_mov_b32_e32 v49, v53
	v_mov_b32_e32 v51, v54
	v_pk_add_f32 v[48:49], v[48:49], v[50:51]
	v_mul_f32_e32 v50, v33, v33
	v_mul_f32_e32 v55, v38, v38
	v_pk_fma_f32 v[50:51], v[32:33], v[32:33], v[50:51] op_sel_hi:[1,1,0]
	v_mul_f32_e32 v54, v35, v35
	v_mul_f32_e32 v56, v39, v39
	v_mov_b32_e32 v51, v55
	v_pk_fma_f32 v[54:55], v[34:35], v[34:35], v[54:55] op_sel_hi:[1,1,0]
	s_nop 0
	v_mov_b32_e32 v55, v56
	v_pk_add_f32 v[50:51], v[50:51], v[54:55]
	s_nop 0
	v_pk_add_f32 v[66:67], v[48:49], v[50:51]
	ds_read_b128 v[48:51], v52 offset:208
	v_pk_add_f32 v[66:67], v[66:67], v[66:67] op_sel:[0,1] op_sel_hi:[1,0]
	s_waitcnt lgkmcnt(0)
	v_pk_mul_f32 v[54:55], v[50:51], v[50:51]
	v_pk_mul_f32 v[56:57], v[48:49], v[48:49]
	s_nop 0
	v_pk_mov_b32 v[58:59], v[56:57], v[54:55] op_sel:[1,0]
	v_mov_b32_e32 v57, v55
	v_pk_add_f32 v[68:69], v[58:59], v[56:57]
	ds_read_b128 v[56:59], v52 offset:224
	ds_read_b128 v[52:55], v52 offset:240
	v_pk_add_f32 v[68:69], v[68:69], v[68:69] op_sel:[0,1] op_sel_hi:[1,0]
	s_waitcnt lgkmcnt(0)
	v_mul_f32_e32 v70, v52, v52
	v_mul_f32_e32 v72, v53, v53
	v_mov_b32_e32 v67, v70
	v_mov_b32_e32 v69, v72
	v_pk_add_f32 v[66:67], v[66:67], v[68:69]
	v_mul_f32_e32 v68, v57, v57
	v_mul_f32_e32 v73, v54, v54
	v_pk_fma_f32 v[68:69], v[56:57], v[56:57], v[68:69] op_sel_hi:[1,1,0]
	v_mul_f32_e32 v70, v59, v59
	v_mul_f32_e32 v74, v55, v55
	v_mov_b32_e32 v69, v73
	v_pk_fma_f32 v[72:73], v[58:59], v[58:59], v[70:71] op_sel_hi:[1,1,0]
	s_nop 0
	v_mov_b32_e32 v73, v74
	v_pk_add_f32 v[68:69], v[68:69], v[72:73]
	s_nop 0
	v_pk_add_f32 v[66:67], v[66:67], v[68:69]
	s_nop 0
	v_add_f32_e32 v66, v66, v67
	v_cndmask_b32_e32 v67, v233, v235, vcc
	v_lshlrev_b32_e32 v67, 2, v67
	ds_bpermute_b32 v67, v67, v66
	s_waitcnt lgkmcnt(0)
	v_add_f32_e32 v66, v66, v67
	v_fmamk_f32 v66, v66, 0x3c000000, v228
	v_cmp_gt_f32_e32 vcc, s31, v66
	v_mul_f32_e32 v67, 0x4f800000, v66
	s_nop 0
	v_cndmask_b32_e32 v66, v66, v67, vcc
	v_sqrt_f32_e32 v67, v66
	s_nop 0
	v_add_u32_e32 v68, -1, v67
	v_fma_f32 v69, -v68, v67, v66
	v_cmp_ge_f32_e64 s[38:39], 0, v69
	v_add_u32_e32 v69, 1, v67
	s_nop 0
	v_cndmask_b32_e64 v68, v67, v68, s[38:39]
	v_fma_f32 v67, -v69, v67, v66
	v_cmp_lt_f32_e64 s[38:39], 0, v67
	s_nop 1
	v_cndmask_b32_e64 v67, v68, v69, s[38:39]
	v_mul_f32_e32 v68, 0x37800000, v67
	v_cndmask_b32_e32 v67, v67, v68, vcc
	v_cmp_class_f32_e32 vcc, v66, v229
	s_nop 1
	v_cndmask_b32_e32 v66, v67, v66, vcc
	v_div_scale_f32 v67, s[8:9], v66, v66, 1.0
	v_rcp_f32_e32 v68, v67
	s_nop 0
	v_fma_f32 v69, -v67, v68, 1.0
	v_fmac_f32_e32 v68, v69, v68
	v_div_scale_f32 v69, vcc, 1.0, v66, 1.0
	v_mul_f32_e32 v70, v69, v68
	v_fma_f32 v72, -v67, v70, v69
	v_fmac_f32_e32 v70, v72, v68
	v_fma_f32 v67, -v67, v70, v69
	v_div_fmas_f32 v67, v67, v68, v70
	v_div_fixup_f32 v66, v67, v66, 1.0
	v_mul_f32_e32 v70, v165, v66
	v_add_u32_e32 v66, s36, v65
	v_ashrrev_i32_e32 v67, 31, v66
	v_lshl_add_u64 v[66:67], s[74:75], 0, v[66:67]
	v_lshlrev_b64 v[66:67], 11, v[66:67]
	v_lshl_add_u64 v[66:67], s[96:97], 0, v[66:67]
	v_lshl_add_u64 v[66:67], v[66:67], 0, s[82:83]
	v_lshl_add_u64 v[68:69], v[66:67], 0, v[128:129]
	v_pk_mul_f32 v[72:73], v[60:61], v[70:71] op_sel_hi:[1,0]
	v_pk_mul_f32 v[74:75], v[62:63], v[70:71] op_sel_hi:[1,0]
	v_pk_mul_f32 v[20:21], v[20:21], v[70:71] op_sel_hi:[1,0]
	v_pk_mul_f32 v[22:23], v[22:23], v[70:71] op_sel_hi:[1,0]
	v_pk_mul_f32 v[0:1], v[0:1], v[70:71] op_sel_hi:[1,0]
	v_pk_mul_f32 v[2:3], v[2:3], v[70:71] op_sel_hi:[1,0]
	v_pk_mul_f32 v[16:17], v[16:17], v[70:71] op_sel_hi:[1,0]
	v_pk_mul_f32 v[18:19], v[18:19], v[70:71] op_sel_hi:[1,0]
	v_pk_mul_f32 v[4:5], v[4:5], v[70:71] op_sel_hi:[1,0]
	v_pk_mul_f32 v[6:7], v[6:7], v[70:71] op_sel_hi:[1,0]
	v_pk_mul_f32 v[8:9], v[8:9], v[70:71] op_sel_hi:[1,0]
	v_pk_mul_f32 v[10:11], v[10:11], v[70:71] op_sel_hi:[1,0]
	s_waitcnt vmcnt(0)
	v_pk_mul_f32 v[62:63], v[136:137], v[22:23]
	v_pk_mul_f32 v[66:67], v[132:133], v[74:75]
	v_pk_mul_f32 v[64:65], v[130:131], v[72:73]
	v_pk_mul_f32 v[22:23], v[134:135], v[20:21]
	v_cvt_pk_bf16_f32 v20, v64, v65
	v_cvt_pk_bf16_f32 v21, v66, v67
	v_cvt_pk_bf16_f32 v22, v22, v23
	v_cvt_pk_bf16_f32 v23, v62, v63
	global_store_dwordx4 v[68:69], v[20:23], off
	v_pk_mul_f32 v[60:61], v[12:13], v[70:71] op_sel_hi:[1,0]
	v_pk_mul_f32 v[62:63], v[14:15], v[70:71] op_sel_hi:[1,0]
	v_pk_mul_f32 v[14:15], v[144:145], v[2:3]
	v_pk_mul_f32 v[22:23], v[140:141], v[62:63]
	v_pk_mul_f32 v[20:21], v[138:139], v[60:61]
	v_pk_mul_f32 v[2:3], v[142:143], v[0:1]
	v_cvt_pk_bf16_f32 v0, v20, v21
	v_cvt_pk_bf16_f32 v1, v22, v23
	v_cvt_pk_bf16_f32 v2, v2, v3
	v_cvt_pk_bf16_f32 v3, v14, v15
	global_store_dwordx4 v[68:69], v[0:3], off offset:16
	v_pk_mul_f32 v[6:7], v[152:153], v[6:7]
	v_pk_mul_f32 v[14:15], v[148:149], v[18:19]
	v_pk_mul_f32 v[12:13], v[146:147], v[16:17]
	v_pk_mul_f32 v[2:3], v[150:151], v[4:5]
	v_cvt_pk_bf16_f32 v0, v12, v13
	v_cvt_pk_bf16_f32 v1, v14, v15
	v_cvt_pk_bf16_f32 v2, v2, v3
	v_cvt_pk_bf16_f32 v3, v6, v7
	global_store_dwordx4 v[68:69], v[0:3], off offset:32
	v_pk_mul_f32 v[6:7], v[156:157], v[10:11]
	v_pk_mul_f32 v[4:5], v[154:155], v[8:9]
	v_pk_mul_f32 v[8:9], v[24:25], v[70:71] op_sel_hi:[1,0]
	v_pk_mul_f32 v[10:11], v[26:27], v[70:71] op_sel_hi:[1,0]
	s_nop 0
	v_pk_mul_f32 v[10:11], v[160:161], v[10:11]
	v_pk_mul_f32 v[2:3], v[158:159], v[8:9]
	v_cvt_pk_bf16_f32 v0, v4, v5
	v_cvt_pk_bf16_f32 v1, v6, v7
	v_cvt_pk_bf16_f32 v2, v2, v3
	v_cvt_pk_bf16_f32 v3, v10, v11
	global_store_dwordx4 v[68:69], v[0:3], off offset:48
	v_pk_mul_f32 v[8:9], v[40:41], v[70:71] op_sel_hi:[1,0]
	v_pk_mul_f32 v[10:11], v[42:43], v[70:71] op_sel_hi:[1,0]
	s_nop 0
	v_pk_mul_f32 v[4:5], v[8:9], v[168:169]
	v_pk_mul_f32 v[6:7], v[10:11], v[170:171]
	v_pk_mul_f32 v[8:9], v[28:29], v[70:71] op_sel_hi:[1,0]
	v_pk_mul_f32 v[10:11], v[30:31], v[70:71] op_sel_hi:[1,0]
	s_nop 0
	v_pk_mul_f32 v[10:11], v[10:11], v[174:175]
	v_pk_mul_f32 v[2:3], v[8:9], v[172:173]
	v_cvt_pk_bf16_f32 v0, v4, v5
	v_cvt_pk_bf16_f32 v1, v6, v7
	v_cvt_pk_bf16_f32 v2, v2, v3
	v_cvt_pk_bf16_f32 v3, v10, v11
	global_store_dwordx4 v[68:69], v[0:3], off offset:64
	v_pk_mul_f32 v[8:9], v[44:45], v[70:71] op_sel_hi:[1,0]
	v_pk_mul_f32 v[10:11], v[46:47], v[70:71] op_sel_hi:[1,0]
	s_nop 0
	v_pk_mul_f32 v[4:5], v[8:9], v[176:177]
	v_pk_mul_f32 v[6:7], v[10:11], v[178:179]
	v_pk_mul_f32 v[8:9], v[32:33], v[70:71] op_sel_hi:[1,0]
	v_pk_mul_f32 v[10:11], v[34:35], v[70:71] op_sel_hi:[1,0]
	s_nop 0
	v_pk_mul_f32 v[10:11], v[10:11], v[182:183]
	v_pk_mul_f32 v[2:3], v[8:9], v[180:181]
	v_cvt_pk_bf16_f32 v0, v4, v5
	v_cvt_pk_bf16_f32 v1, v6, v7
	v_cvt_pk_bf16_f32 v2, v2, v3
	v_cvt_pk_bf16_f32 v3, v10, v11
	global_store_dwordx4 v[68:69], v[0:3], off offset:80
	v_pk_mul_f32 v[8:9], v[36:37], v[70:71] op_sel_hi:[1,0]
	v_pk_mul_f32 v[10:11], v[38:39], v[70:71] op_sel_hi:[1,0]
	s_nop 0
	v_pk_mul_f32 v[4:5], v[8:9], v[184:185]
	v_pk_mul_f32 v[6:7], v[10:11], v[186:187]
	v_pk_mul_f32 v[8:9], v[48:49], v[70:71] op_sel_hi:[1,0]
	v_pk_mul_f32 v[10:11], v[50:51], v[70:71] op_sel_hi:[1,0]
	s_nop 0
	v_pk_mul_f32 v[10:11], v[10:11], v[190:191]
	v_pk_mul_f32 v[2:3], v[8:9], v[188:189]
	v_cvt_pk_bf16_f32 v0, v4, v5
	v_cvt_pk_bf16_f32 v1, v6, v7
	v_cvt_pk_bf16_f32 v2, v2, v3
	v_cvt_pk_bf16_f32 v3, v10, v11
	global_store_dwordx4 v[68:69], v[0:3], off offset:96
	v_pk_mul_f32 v[8:9], v[56:57], v[70:71] op_sel_hi:[1,0]
	v_pk_mul_f32 v[10:11], v[58:59], v[70:71] op_sel_hi:[1,0]
	s_nop 0
	v_pk_mul_f32 v[4:5], v[8:9], v[192:193]
	v_pk_mul_f32 v[6:7], v[10:11], v[194:195]
	v_pk_mul_f32 v[8:9], v[52:53], v[70:71] op_sel_hi:[1,0]
	v_pk_mul_f32 v[10:11], v[54:55], v[70:71] op_sel_hi:[1,0]
	s_nop 0
	v_pk_mul_f32 v[10:11], v[10:11], v[198:199]
	v_pk_mul_f32 v[2:3], v[8:9], v[196:197]
	v_cvt_pk_bf16_f32 v0, v4, v5
	v_cvt_pk_bf16_f32 v1, v6, v7
	v_cvt_pk_bf16_f32 v2, v2, v3
	v_cvt_pk_bf16_f32 v3, v10, v11
	global_store_dwordx4 v[68:69], v[0:3], off offset:112
	s_branch .LBB0_164
